# top-k items mapped per XCD (token tiles whose queries the XCD projected) and a third XCD-local barrier for phase 9->10
# speedup vs baseline: 1.0021x; 1.0007x over previous
.LBB0_671:
	s_cmp_lt_i32 s55, 11
	s_cbranch_scc1 .LBB0_725
	s_waitcnt vmcnt(0) lgkmcnt(0)
	s_barrier
	v_mov_b32_e32 v0, 8
	ds_read_b32 v1, v0
	s_waitcnt lgkmcnt(0)
	v_readfirstlane_b32 s3, v1
	s_nop 3
	s_barrier
	s_cmp_lg_u32 s3, 0
	s_cbranch_scc1 .Lxl9a_have
	s_and_saveexec_b64 s[6:7], s[4:5]
	s_cbranch_execz .Lxl9a_m1
	v_mov_b32_e32 v0, 0
	global_load_dword v1, v0, s[46:47] offset:1152 sc1
	global_load_dword v2, v0, s[46:47] offset:1408 sc1
	global_load_dword v3, v0, s[46:47] offset:1664 sc1
	global_load_dword v4, v0, s[46:47] offset:1920 sc1
	global_load_dword v5, v0, s[46:47] offset:2176 sc1
	global_load_dword v6, v0, s[46:47] offset:2432 sc1
	global_load_dword v7, v0, s[46:47] offset:2688 sc1
	global_load_dword v8, v0, s[46:47] offset:2944 sc1
	s_waitcnt vmcnt(0)
	v_or3_b32 v9, v1, v2, v3
	v_or3_b32 v9, v9, v4, v5
	v_or3_b32 v9, v9, v6, v7
	v_or_b32_e32 v9, v9, v8
	v_mov_b32_e32 v11, 0
	v_add_u32_e32 v10, -1, v1
	v_and_b32_e32 v10, v10, v1
	v_or_b32_e32 v11, v11, v10
	v_add_u32_e32 v10, -1, v2
	v_and_b32_e32 v10, v10, v2
	v_or_b32_e32 v11, v11, v10
	v_add_u32_e32 v10, -1, v3
	v_and_b32_e32 v10, v10, v3
	v_or_b32_e32 v11, v11, v10
	v_add_u32_e32 v10, -1, v4
	v_and_b32_e32 v10, v10, v4
	v_or_b32_e32 v11, v11, v10
	v_add_u32_e32 v10, -1, v5
	v_and_b32_e32 v10, v10, v5
	v_or_b32_e32 v11, v11, v10
	v_add_u32_e32 v10, -1, v6
	v_and_b32_e32 v10, v10, v6
	v_or_b32_e32 v11, v11, v10
	v_add_u32_e32 v10, -1, v7
	v_and_b32_e32 v10, v10, v7
	v_or_b32_e32 v11, v11, v10
	v_add_u32_e32 v10, -1, v8
	v_and_b32_e32 v10, v10, v8
	v_or_b32_e32 v11, v11, v10
	s_nop 1
	v_readfirstlane_b32 s8, v9
	v_readfirstlane_b32 s9, v11
	s_nop 3
	s_cmp_eq_u32 s8, 0xff
	s_cselect_b32 s11, 1, 0
	s_cmp_eq_u32 s9, 0
	s_cselect_b32 s11, s11, 0
	s_cmp_eq_u32 s52, 0x200
	s_cselect_b32 s11, s11, 0
	s_cmp_eq_u32 s11, 1
	s_cselect_b32 s10, 1, 2
	v_mov_b32_e32 v0, 8
	v_mov_b32_e32 v1, s10
	ds_write_b32 v0, v1
	s_waitcnt lgkmcnt(0)

.LBB0_725:
	s_cmp_gt_i32 s54, 10
	s_cselect_b64 s[6:7], -1, 0
	s_cmp_lt_i32 s55, 11
	s_cselect_b64 s[8:9], -1, 0
	s_or_b64 s[6:7], s[6:7], s[8:9]
	s_and_b64 vcc, exec, s[6:7]
	s_cbranch_vccnz .LBB0_909
	s_cmpk_gt_i32 s2, 0x7ff
	s_cbranch_scc1 .LBB0_855
	s_mov_b32 s100, s2
	s_mov_b32 s94, s52
	s_movk_i32 s101, 0x800
	s_cmp_eq_u32 s52, 0x200
	s_cbranch_scc0 .Lp10_nomap
	s_and_b32 s100, s2, 7
	s_lshl_b32 s100, s100, 8
	s_add_u32 s101, s100, 0x100
	s_lshr_b32 s94, s2, 3
	s_add_u32 s100, s100, s94
	s_mov_b32 s94, 64
.Lp10_nomap:
	s_load_dwordx2 s[16:17], s[0:1], 0xa0
	s_load_dwordx2 s[18:19], s[0:1], 0xd0
	s_load_dwordx2 s[20:21], s[0:1], 0x108
	v_lshrrev_b32_e32 v59, 4, v168
	v_lshlrev_b32_e32 v0, 3, v168
	v_mov_b32_e32 v53, 0
	v_and_b32_e32 v58, 0x78, v0
	s_waitcnt lgkmcnt(0)
	s_add_u32 s22, s20, 0x800000
	s_addc_u32 s23, s21, 0
	s_and_b32 s9, s100, 7
	s_add_i32 s8, 16, 0x10c00
	s_lshl_b32 s3, s9, 16
	s_add_u32 s6, s18, s3
	v_lshlrev_b32_e32 v52, 8, v59
	s_addc_u32 s7, s19, 0
	v_lshlrev_b32_e32 v2, 1, v58
	v_mov_b32_e32 v3, v53
	v_lshl_add_u64 v[4:5], s[6:7], 0, v[52:53]
	v_lshl_add_u64 v[54:55], v[4:5], 0, v[2:3]
	s_movk_i32 s36, 0x7000
	v_add_co_u32_e32 v28, vcc, s36, v54
	v_lshrrev_b32_e32 v82, 2, v168
	s_lshl_b32 s3, s100, 3
	v_addc_co_u32_e32 v29, vcc, 0, v55, vcc
	s_movk_i32 s37, 0x6000
	v_and_b32_e32 v63, 0xf0, v82
	s_and_b32 s6, s3, 0xffffffc0
	v_add_co_u32_e32 v30, vcc, s37, v54
	v_add_u32_e32 v1, s6, v63
	s_nop 0
	v_addc_co_u32_e32 v31, vcc, 0, v55, vcc
	s_movk_i32 s6, 0x5000
	v_add_co_u32_e32 v36, vcc, s6, v54
	v_and_b32_e32 v71, 15, v168
	s_nop 0
	v_addc_co_u32_e32 v37, vcc, 0, v55, vcc
	s_movk_i32 s38, 0x4000
	v_or_b32_e32 v4, v1, v71
	v_add_co_u32_e32 v38, vcc, s38, v54
	v_ashrrev_i32_e32 v5, 31, v4
	s_nop 0
	v_addc_co_u32_e32 v39, vcc, 0, v55, vcc
	s_movk_i32 s6, 0x3000
	v_lshlrev_b64 v[4:5], 12, v[4:5]
	v_add_co_u32_e32 v44, vcc, s6, v54
	v_bfe_u32 v61, v168, 4, 2
	s_mov_b32 s25, 0
	v_lshl_add_u64 v[4:5], s[16:17], 0, v[4:5]
	s_lshl_b32 s24, s9, 9
	v_addc_co_u32_e32 v45, vcc, 0, v55, vcc
	s_movk_i32 s39, 0x2000
	v_lshlrev_b32_e32 v0, 4, v61
	v_lshl_add_u64 v[4:5], v[4:5], 0, s[24:25]
	v_mov_b32_e32 v1, v53
	v_add_co_u32_e32 v46, vcc, s39, v54
	v_lshl_add_u64 v[20:21], v[4:5], 0, v[0:1]
	s_nop 0
	v_addc_co_u32_e32 v47, vcc, 0, v55, vcc
	s_movk_i32 s6, 0x1000
	global_load_dwordx4 v[4:7], v[20:21], off offset:192
	global_load_dwordx4 v[8:11], v[20:21], off offset:128
	global_load_dwordx4 v[12:15], v[20:21], off offset:64
	global_load_dwordx4 v[16:19], v[20:21], off
	v_add_co_u32_e32 v56, vcc, s6, v54
	global_load_dwordx4 v[24:27], v[28:29], off
	global_load_dwordx4 v[20:23], v[30:31], off
	v_addc_co_u32_e32 v57, vcc, 0, v55, vcc
	global_load_dwordx4 v[32:35], v[36:37], off
	global_load_dwordx4 v[28:31], v[38:39], off
	global_load_dwordx4 v[40:43], v[44:45], off
	s_nop 0
	global_load_dwordx4 v[36:39], v[46:47], off
	s_nop 0
	global_load_dwordx4 v[44:47], v[56:57], off
	global_load_dwordx4 v[48:51], v[54:55], off
	v_mbcnt_lo_u32_b32 v1, -1, 0
	v_lshl_add_u64 v[54:55], s[18:19], 0, v[52:53]
	v_mbcnt_hi_u32_b32 v1, -1, v1
	v_lshl_add_u64 v[54:55], v[54:55], 0, v[2:3]
	v_and_b32_e32 v3, 64, v1
	v_add_u32_e32 v64, 16, v2
	v_xor_b32_e32 v2, 1, v1
	v_add_u32_e32 v3, 64, v3
	v_cmp_lt_i32_e32 vcc, v2, v3
	v_and_b32_e32 v83, 3, v168
	s_movk_i32 s9, 0x110
	v_cndmask_b32_e32 v2, v1, v2, vcc
	v_lshlrev_b32_e32 v96, 2, v2
	v_xor_b32_e32 v2, 2, v1
	v_add_u32_e32 v65, 16, v0
	v_lshl_or_b32 v0, v61, 2, v63
	s_movk_i32 s6, 0x210
	v_cmp_lt_i32_e32 vcc, v2, v3
	v_lshlrev_b32_e32 v60, 7, v59
	v_lshlrev_b32_e32 v62, 3, v61
	v_or_b32_e32 v84, v63, v71
	v_mul_u32_u24_e32 v59, 0x110, v59
	v_mad_u32_u24 v85, v82, s6, 16
	v_mul_u32_u24_e32 v61, 0x110, v71
	v_mad_u32_u24 v88, v71, s9, v65
	v_lshl_add_u32 v63, v71, 2, 16
	v_mul_u32_u24_e32 v66, 0x210, v0
	v_lshlrev_b32_e32 v0, 4, v83
	v_cndmask_b32_e32 v1, v1, v2, vcc
	v_lshl_add_u32 v86, v82, 5, s8
	v_lshl_add_u32 v87, v83, 7, v85
	v_cmp_eq_u32_e64 s[6:7], 2, v83
	v_add_u32_e32 v89, 0x1100, v88
	v_add_u32_e32 v90, 0x2200, v88
	v_add_u32_e32 v91, 0x3300, v88
	v_add_u32_e32 v92, 0x4400, v88
	v_add_u32_e32 v93, 0x5500, v88
	v_add_u32_e32 v94, 0x6600, v88
	v_add_u32_e32 v95, 0x7700, v88
	v_cmp_eq_u32_e64 s[8:9], 3, v83
	v_cmp_ne_u32_e64 s[10:11], 3, v83
	v_cmp_gt_u32_e64 s[12:13], 2, v83
	v_cmp_eq_u32_e64 s[14:15], 0, v83
	v_lshlrev_b32_e32 v97, 2, v1
	v_mov_b32_e32 v1, v0
	v_mov_b32_e32 v2, v0
	v_mov_b32_e32 v3, v0
	v_mov_b32_e32 v56, v0
	v_mov_b32_e32 v57, v0
	s_lshl_b32 s40, s100, 4
	s_lshl_b32 s41, s94, 4
	s_lshl_b32 s42, s94, 3
	s_movk_i32 s43, 0xff80
	s_movk_i32 s44, 0x7f
	s_movk_i32 s45, 0x6f
	s_movk_i32 s48, 0x5f
	s_movk_i32 s49, 0x4f
	v_lshlrev_b32_e32 v52, 1, v60
	v_lshlrev_b32_e32 v58, 1, v58
	s_mov_b32 s50, 0x9000
	s_mov_b32 s51, 0xb000
	s_mov_b32 s56, 0xd000
	s_mov_b32 s57, 0xf000
	v_lshlrev_b32_e32 v60, 1, v62
	s_movk_i32 s58, 0xff00
	v_add_u32_e32 v98, v64, v59
	v_add_u32_e32 v99, v65, v61
	v_add_u32_e32 v100, v63, v66
	v_bfrev_b32_e32 v101, 1
	s_mov_b32 s59, s100
	s_mov_b32 s80, s2
	s_load_dwordx2 s[88:89], s[0:1], 0x88
	s_load_dwordx2 s[96:97], s[0:1], 0x90
	s_load_dwordx2 s[98:99], s[0:1], 0xf8
	v_lshlrev_b32_e32 v234, 4, v168
	v_lshlrev_b32_e32 v235, 2, v168
	s_waitcnt lgkmcnt(0)
	s_branch .LBB0_729

.LBB0_761:
	s_or_b64 exec, exec, s[26:27]
	s_waitcnt lgkmcnt(0)
	s_barrier
	s_waitcnt vmcnt(27)
	ds_write_b128 v98, v[16:19]
	s_waitcnt vmcnt(26)
	ds_write_b128 v98, v[20:23] offset:4352
	s_waitcnt vmcnt(25)
	ds_write_b128 v98, v[24:27] offset:8704
	s_waitcnt vmcnt(24)
	ds_write_b128 v98, v[28:31] offset:13056
	s_waitcnt vmcnt(23)
	ds_write_b128 v98, v[36:39] offset:17408
	s_waitcnt vmcnt(22)
	ds_write_b128 v98, v[40:43] offset:21760
	s_waitcnt vmcnt(21)
	ds_write_b128 v98, v[44:47] offset:26112
	s_waitcnt vmcnt(20)
	ds_write_b128 v98, v[48:51] offset:30464
	s_waitcnt lgkmcnt(0)
	s_barrier
	ds_read_b128 v[16:19], v99
	ds_read_b128 v[20:23], v99 offset:4352
	ds_read_b128 v[24:27], v99 offset:8704
	ds_read_b128 v[28:31], v99 offset:13056
	ds_read_b128 v[36:39], v99 offset:17408
	ds_read_b128 v[40:43], v99 offset:21760
	ds_read_b128 v[44:47], v99 offset:26112
	ds_read_b128 v[48:51], v99 offset:30464
	s_waitcnt vmcnt(19) lgkmcnt(7)
	v_mfma_f32_16x16x32_bf16 v[16:19], v[32:35], v[16:19], 0
	s_add_i32 s59, s59, s94
	s_cmp_ge_i32 s59, s101
	s_cselect_b64 s[26:27], -1, 0
	s_waitcnt lgkmcnt(6)
	v_mfma_f32_16x16x32_bf16 v[20:23], v[32:35], v[20:23], 0
	s_cmp_lt_i32 s59, s101
	s_cselect_b32 s28, s59, s100
	s_and_b32 s29, s28, 7
	s_waitcnt lgkmcnt(5)
	v_mfma_f32_16x16x32_bf16 v[24:27], v[32:35], v[24:27], 0
	s_lshl_b32 s24, s29, 16
	s_waitcnt lgkmcnt(4)
	v_mfma_f32_16x16x32_bf16 v[28:31], v[32:35], v[28:31], 0
	s_waitcnt lgkmcnt(3)
	v_mfma_f32_16x16x32_bf16 v[36:39], v[32:35], v[36:39], 0
	s_waitcnt lgkmcnt(2)
	v_mfma_f32_16x16x32_bf16 v[40:43], v[32:35], v[40:43], 0
	s_waitcnt lgkmcnt(1)
	v_mfma_f32_16x16x32_bf16 v[44:47], v[32:35], v[44:47], 0
	s_waitcnt lgkmcnt(0)
	v_mfma_f32_16x16x32_bf16 v[32:35], v[32:35], v[48:51], 0
	ds_read_b128 v[48:51], v88 offset:64
	ds_read_b128 v[102:105], v88 offset:128
	s_waitcnt vmcnt(18) lgkmcnt(1)
	v_mfma_f32_16x16x32_bf16 v[16:19], v[12:15], v[48:51], v[16:19]
	ds_read_b128 v[48:51], v89 offset:64
	ds_read_b128 v[106:109], v88 offset:192
	s_waitcnt lgkmcnt(1)
	v_mfma_f32_16x16x32_bf16 v[20:23], v[12:15], v[48:51], v[20:23]
	ds_read_b128 v[48:51], v90 offset:64
	ds_read_b128 v[110:113], v90 offset:128
	s_waitcnt lgkmcnt(1)
	v_mfma_f32_16x16x32_bf16 v[24:27], v[12:15], v[48:51], v[24:27]
	ds_read_b128 v[48:51], v91 offset:64
	ds_read_b128 v[114:117], v90 offset:192
	s_waitcnt vmcnt(17)
	v_mfma_f32_16x16x32_bf16 v[16:19], v[8:11], v[102:105], v[16:19]
	s_waitcnt lgkmcnt(1)
	v_mfma_f32_16x16x32_bf16 v[28:31], v[12:15], v[48:51], v[28:31]
	ds_read_b128 v[48:51], v92 offset:64
	ds_read_b128 v[118:121], v93 offset:64
	ds_read_b128 v[122:125], v92 offset:128
	s_waitcnt vmcnt(16)
	v_mfma_f32_16x16x32_bf16 v[16:19], v[4:7], v[106:109], v[16:19]
	s_waitcnt lgkmcnt(2)
	v_mfma_f32_16x16x32_bf16 v[36:39], v[12:15], v[48:51], v[36:39]
	ds_read_b128 v[48:51], v94 offset:64
	ds_read_b128 v[126:129], v94 offset:128
	ds_read_b128 v[130:133], v92 offset:192
	s_nop 2
	v_not_b32_e32 v61, v16
	v_or_b32_e32 v80, 0x80000000, v16
	s_waitcnt lgkmcnt(4)
	v_mfma_f32_16x16x32_bf16 v[40:43], v[12:15], v[118:121], v[40:43]
	ds_read_b128 v[118:121], v89 offset:128
	ds_read_b128 v[134:137], v89 offset:192
	ds_read_b128 v[138:141], v91 offset:128
	ds_read_b128 v[146:149], v91 offset:192
	ds_read_b128 v[102:105], v93 offset:128
	ds_read_b128 v[150:153], v93 offset:192
	ds_read_b128 v[154:157], v95 offset:64
	ds_read_b128 v[158:161], v94 offset:192
	v_cmp_gt_i32_e32 vcc, 0, v16
	s_waitcnt lgkmcnt(10)
	v_mfma_f32_16x16x32_bf16 v[44:47], v[12:15], v[48:51], v[44:47]
	ds_read_b128 v[106:109], v95 offset:128
	ds_read_b128 v[162:165], v95 offset:192
	v_cndmask_b32_e32 v16, v80, v61, vcc
	v_and_b32_e32 v16, 0xffffff80, v16
	s_waitcnt lgkmcnt(3)
	v_mfma_f32_16x16x32_bf16 v[12:15], v[12:15], v[154:157], v[32:35]
	v_bitop3_b32 v48, v71, s44, v16 bitop3:0x36
	v_not_b32_e32 v16, v17
	v_cmp_gt_i32_e32 vcc, 0, v17
	v_or_b32_e32 v32, 0x80000000, v17
	v_or_b32_e32 v17, 0x80000000, v18
	v_cndmask_b32_e32 v16, v32, v16, vcc
	v_and_b32_e32 v16, 0xffffff80, v16
	v_bitop3_b32 v49, v71, s44, v16 bitop3:0x36
	v_not_b32_e32 v16, v18
	v_cmp_gt_i32_e32 vcc, 0, v18
	v_mfma_f32_16x16x32_bf16 v[20:23], v[8:11], v[118:121], v[20:23]
	v_mov_b32_e32 v61, v53
	v_cndmask_b32_e32 v16, v17, v16, vcc
	v_and_b32_e32 v16, 0xffffff80, v16
	v_bitop3_b32 v50, v71, s44, v16 bitop3:0x36
	v_not_b32_e32 v16, v19
	v_or_b32_e32 v17, 0x80000000, v19
	v_cmp_gt_i32_e32 vcc, 0, v19
	v_mfma_f32_16x16x32_bf16 v[32:35], v[8:11], v[122:125], v[36:39]
	s_nop 0
	v_cndmask_b32_e32 v16, v17, v16, vcc
	v_mfma_f32_16x16x32_bf16 v[36:39], v[8:11], v[102:105], v[40:43]
	s_nop 2
	v_and_b32_e32 v40, 0xffffff80, v16
	v_mfma_f32_16x16x32_bf16 v[16:19], v[4:7], v[134:137], v[20:23]
	v_bitop3_b32 v40, v71, s44, v40 bitop3:0x36
	v_mfma_f32_16x16x32_bf16 v[24:27], v[8:11], v[110:113], v[24:27]
	v_mfma_f32_16x16x32_bf16 v[28:31], v[8:11], v[138:141], v[28:31]
	s_nop 4
	v_not_b32_e32 v41, v16
	v_or_b32_e32 v42, 0x80000000, v16
	v_cmp_gt_i32_e32 vcc, 0, v16
	v_mfma_f32_16x16x32_bf16 v[20:23], v[8:11], v[126:129], v[44:47]
	s_nop 0
	v_cndmask_b32_e32 v16, v42, v41, vcc
	v_and_b32_e32 v16, 0xffffff80, v16
	v_bitop3_b32 v16, v71, s45, v16 bitop3:0x36
	ds_write2_b32 v77, v48, v16 offset1:16
	v_not_b32_e32 v16, v17
	v_or_b32_e32 v41, 0x80000000, v17
	v_cmp_gt_i32_e32 vcc, 0, v17
	v_or_b32_e32 v17, 0x80000000, v18
	s_waitcnt lgkmcnt(2)
	v_mfma_f32_16x16x32_bf16 v[8:11], v[8:11], v[106:109], v[12:15]
	v_cndmask_b32_e32 v16, v41, v16, vcc
	v_and_b32_e32 v16, 0xffffff80, v16
	v_bitop3_b32 v16, v71, s45, v16 bitop3:0x36
	ds_write2_b32 v77, v49, v16 offset0:132 offset1:148
	v_not_b32_e32 v16, v18
	v_cmp_gt_i32_e32 vcc, 0, v18
	v_mfma_f32_16x16x32_bf16 v[12:15], v[4:7], v[114:117], v[24:27]
	s_nop 0
	v_cndmask_b32_e32 v16, v17, v16, vcc
	v_and_b32_e32 v16, 0xffffff80, v16
	v_bitop3_b32 v16, v71, s45, v16 bitop3:0x36
	ds_write2_b32 v78, v50, v16 offset0:8 offset1:24
	v_not_b32_e32 v16, v19
	v_or_b32_e32 v17, 0x80000000, v19
	v_cmp_gt_i32_e32 vcc, 0, v19
	v_mfma_f32_16x16x32_bf16 v[24:27], v[4:7], v[146:149], v[28:31]
	s_nop 0
	v_cndmask_b32_e32 v16, v17, v16, vcc
	v_cmp_gt_i32_e32 vcc, 0, v12
	v_mfma_f32_16x16x32_bf16 v[28:31], v[4:7], v[130:133], v[32:35]
	v_mfma_f32_16x16x32_bf16 v[32:35], v[4:7], v[150:153], v[36:39]
	v_mfma_f32_16x16x32_bf16 v[20:23], v[4:7], v[158:161], v[20:23]
	s_waitcnt lgkmcnt(3)
	v_mfma_f32_16x16x32_bf16 v[4:7], v[4:7], v[162:165], v[8:11]
	s_nop 2
	v_and_b32_e32 v8, 0xffffff80, v16
	v_bitop3_b32 v8, v71, s45, v8 bitop3:0x36
	ds_write2_b32 v78, v40, v8 offset0:140 offset1:156
	v_not_b32_e32 v8, v12
	v_or_b32_e32 v9, 0x80000000, v12
	v_cndmask_b32_e32 v8, v9, v8, vcc
	v_not_b32_e32 v9, v13
	v_or_b32_e32 v10, 0x80000000, v13
	v_cmp_gt_i32_e32 vcc, 0, v13
	v_or_b32_e32 v11, 0x80000000, v14
	v_or_b32_e32 v12, 0x80000000, v15
	v_cndmask_b32_e32 v9, v10, v9, vcc
	v_not_b32_e32 v10, v14
	v_cmp_gt_i32_e32 vcc, 0, v14
	v_or_b32_e32 v13, 0x80000000, v24
	v_and_b32_e32 v8, 0xffffff80, v8
	v_cndmask_b32_e32 v10, v11, v10, vcc
	v_not_b32_e32 v11, v15
	v_cmp_gt_i32_e32 vcc, 0, v15
	v_bitop3_b32 v8, v71, s48, v8 bitop3:0x36
	v_and_b32_e32 v9, 0xffffff80, v9
	v_cndmask_b32_e32 v11, v12, v11, vcc
	v_not_b32_e32 v12, v24
	v_cmp_gt_i32_e32 vcc, 0, v24
	v_bitop3_b32 v9, v71, s48, v9 bitop3:0x36
	v_and_b32_e32 v10, 0xffffff80, v10
	v_cndmask_b32_e32 v12, v13, v12, vcc
	v_and_b32_e32 v12, 0xffffff80, v12
	v_bitop3_b32 v12, v71, s49, v12 bitop3:0x36
	ds_write2_b32 v77, v8, v12 offset0:32 offset1:48
	v_not_b32_e32 v8, v25
	v_or_b32_e32 v12, 0x80000000, v25
	v_cmp_gt_i32_e32 vcc, 0, v25
	v_bitop3_b32 v10, v71, s48, v10 bitop3:0x36
	v_and_b32_e32 v11, 0xffffff80, v11
	v_cndmask_b32_e32 v8, v12, v8, vcc
	v_and_b32_e32 v8, 0xffffff80, v8
	v_bitop3_b32 v8, v71, s49, v8 bitop3:0x36
	ds_write2_b32 v77, v9, v8 offset0:164 offset1:180
	v_not_b32_e32 v8, v26
	v_or_b32_e32 v9, 0x80000000, v26
	v_cmp_gt_i32_e32 vcc, 0, v26
	v_bitop3_b32 v11, v71, s48, v11 bitop3:0x36
	v_or_b32_e32 v12, 0x80000000, v31
	v_cndmask_b32_e32 v8, v9, v8, vcc
	v_and_b32_e32 v8, 0xffffff80, v8
	v_bitop3_b32 v8, v71, s49, v8 bitop3:0x36
	ds_write2_b32 v78, v10, v8 offset0:40 offset1:56
	v_not_b32_e32 v8, v27
	v_or_b32_e32 v9, 0x80000000, v27
	v_cmp_gt_i32_e32 vcc, 0, v27
	v_or_b32_e32 v10, 0x80000000, v29
	v_or_b32_e32 v13, 0x80000000, v32
	v_cndmask_b32_e32 v8, v9, v8, vcc
	v_and_b32_e32 v8, 0xffffff80, v8
	v_bitop3_b32 v8, v71, s49, v8 bitop3:0x36
	ds_write2_b32 v78, v11, v8 offset0:172 offset1:188
	v_not_b32_e32 v8, v28
	v_or_b32_e32 v9, 0x80000000, v28
	v_cmp_gt_i32_e32 vcc, 0, v28
	v_or_b32_e32 v11, 0x80000000, v30
	s_nop 0
	v_cndmask_b32_e32 v8, v9, v8, vcc
	v_not_b32_e32 v9, v29
	v_cmp_gt_i32_e32 vcc, 0, v29
	v_and_b32_e32 v8, 0xffffff80, v8
	v_bitop3_b32 v8, v71, 63, v8 bitop3:0x36
	v_cndmask_b32_e32 v9, v10, v9, vcc
	v_not_b32_e32 v10, v30
	v_cmp_gt_i32_e32 vcc, 0, v30
	v_and_b32_e32 v9, 0xffffff80, v9
	v_bitop3_b32 v9, v71, 63, v9 bitop3:0x36
	v_cndmask_b32_e32 v10, v11, v10, vcc
	v_not_b32_e32 v11, v31
	v_cmp_gt_i32_e32 vcc, 0, v31
	v_and_b32_e32 v10, 0xffffff80, v10
	v_bitop3_b32 v10, v71, 63, v10 bitop3:0x36
	v_cndmask_b32_e32 v11, v12, v11, vcc
	v_not_b32_e32 v12, v32
	v_cmp_gt_i32_e32 vcc, 0, v32
	v_and_b32_e32 v11, 0xffffff80, v11
	v_bitop3_b32 v11, v71, 63, v11 bitop3:0x36
	v_cndmask_b32_e32 v12, v13, v12, vcc
	v_and_b32_e32 v12, 0xffffff80, v12
	v_bitop3_b32 v12, v71, 47, v12 bitop3:0x36
	ds_write2_b32 v77, v8, v12 offset0:64 offset1:80
	v_not_b32_e32 v8, v33
	v_or_b32_e32 v12, 0x80000000, v33
	v_cmp_gt_i32_e32 vcc, 0, v33
	v_or_b32_e32 v13, 0x80000000, v4
	s_nop 0
	v_cndmask_b32_e32 v8, v12, v8, vcc
	v_and_b32_e32 v8, 0xffffff80, v8
	v_bitop3_b32 v8, v71, 47, v8 bitop3:0x36
	ds_write2_b32 v77, v9, v8 offset0:196 offset1:212
	v_not_b32_e32 v8, v34
	v_or_b32_e32 v9, 0x80000000, v34
	v_cmp_gt_i32_e32 vcc, 0, v34
	v_or_b32_e32 v12, 0x80000000, v23
	s_nop 0
	v_cndmask_b32_e32 v8, v9, v8, vcc
	v_and_b32_e32 v8, 0xffffff80, v8
	v_bitop3_b32 v8, v71, 47, v8 bitop3:0x36
	ds_write2_b32 v78, v10, v8 offset0:72 offset1:88
	v_not_b32_e32 v8, v35
	v_or_b32_e32 v9, 0x80000000, v35
	v_cmp_gt_i32_e32 vcc, 0, v35
	v_or_b32_e32 v10, 0x80000000, v21
	s_nop 0
	v_cndmask_b32_e32 v8, v9, v8, vcc
	v_and_b32_e32 v8, 0xffffff80, v8
	v_bitop3_b32 v8, v71, 47, v8 bitop3:0x36
	ds_write2_b32 v78, v11, v8 offset0:204 offset1:220
	v_not_b32_e32 v8, v20
	v_or_b32_e32 v9, 0x80000000, v20
	v_cmp_gt_i32_e32 vcc, 0, v20
	v_or_b32_e32 v11, 0x80000000, v22
	s_nop 0
	v_cndmask_b32_e32 v8, v9, v8, vcc
	v_not_b32_e32 v9, v21
	v_cmp_gt_i32_e32 vcc, 0, v21
	v_and_b32_e32 v8, 0xffffff80, v8
	v_bitop3_b32 v8, v71, 31, v8 bitop3:0x36
	v_cndmask_b32_e32 v9, v10, v9, vcc
	v_not_b32_e32 v10, v22
	v_cmp_gt_i32_e32 vcc, 0, v22
	v_and_b32_e32 v9, 0xffffff80, v9
	v_bitop3_b32 v9, v71, 31, v9 bitop3:0x36
	v_cndmask_b32_e32 v10, v11, v10, vcc
	v_not_b32_e32 v11, v23
	v_cmp_gt_i32_e32 vcc, 0, v23
	v_and_b32_e32 v10, 0xffffff80, v10
	v_bitop3_b32 v10, v71, 31, v10 bitop3:0x36
	v_cndmask_b32_e32 v11, v12, v11, vcc
	v_not_b32_e32 v12, v4
	v_cmp_gt_i32_e32 vcc, 0, v4
	v_and_b32_e32 v11, 0xffffff80, v11
	v_bitop3_b32 v11, v71, 31, v11 bitop3:0x36
	v_cndmask_b32_e32 v4, v13, v12, vcc
	v_and_b32_e32 v4, 0xffffff80, v4
	v_bitop3_b32 v4, v71, 15, v4 bitop3:0x36
	ds_write2_b32 v77, v8, v4 offset0:96 offset1:112
	v_not_b32_e32 v4, v5
	v_or_b32_e32 v8, 0x80000000, v5
	v_cmp_gt_i32_e32 vcc, 0, v5
	v_or_b32_e32 v5, 0x80000000, v6
	s_nop 0
	v_cndmask_b32_e32 v4, v8, v4, vcc
	v_and_b32_e32 v4, 0xffffff80, v4
	v_bitop3_b32 v4, v71, 15, v4 bitop3:0x36
	ds_write2_b32 v77, v9, v4 offset0:228 offset1:244
	v_not_b32_e32 v4, v6
	v_cmp_gt_i32_e32 vcc, 0, v6
	s_nop 1
	v_cndmask_b32_e32 v4, v5, v4, vcc
	v_and_b32_e32 v4, 0xffffff80, v4
	v_bitop3_b32 v4, v71, 15, v4 bitop3:0x36
	ds_write2_b32 v78, v10, v4 offset0:104 offset1:120
	v_not_b32_e32 v4, v7
	v_or_b32_e32 v5, 0x80000000, v7
	v_cmp_gt_i32_e32 vcc, 0, v7
	s_nop 1
	v_cndmask_b32_e32 v4, v5, v4, vcc
	v_and_b32_e32 v4, 0xffffff80, v4
	v_bitop3_b32 v4, v71, 15, v4 bitop3:0x36
	ds_write2_b32 v78, v11, v4 offset0:236 offset1:252
	v_lshl_add_u64 v[4:5], v[54:55], 0, s[24:25]
	v_add_co_u32_e32 v6, vcc, s39, v4
	s_waitcnt lgkmcnt(0)
	s_nop 0
	v_addc_co_u32_e32 v7, vcc, 0, v5, vcc
	s_waitcnt vmcnt(0)
	v_mul_f32_e32 v170, s86, v170
	v_mul_f32_e32 v171, s86, v171
	v_mul_f32_e32 v172, s86, v172
	v_mul_f32_e32 v173, s86, v173
	v_mul_f32_e32 v174, s86, v174
	v_mul_f32_e32 v175, s86, v175
	v_mul_f32_e32 v176, s86, v176
	v_mul_f32_e32 v177, s86, v177
	v_mul_f32_e32 v178, s86, v178
	v_mul_f32_e32 v179, s86, v179
	v_mul_f32_e32 v180, s86, v180
	v_mul_f32_e32 v181, s86, v181
	v_mul_f32_e32 v182, s86, v182
	v_mul_f32_e32 v183, s86, v183
	v_mul_f32_e32 v184, s86, v184
	v_mul_f32_e32 v185, s86, v185
	v_mul_f32_e32 v186, s86, v186
	v_mul_f32_e32 v187, s86, v187
	v_mul_f32_e32 v188, s86, v188
	v_mul_f32_e32 v189, s86, v189
	v_mul_f32_e32 v190, s86, v190
	v_mul_f32_e32 v191, s86, v191
	v_mul_f32_e32 v192, s86, v192
	v_mul_f32_e32 v193, s86, v193
	v_mul_f32_e32 v194, s86, v194
	v_mul_f32_e32 v195, s86, v195
	v_mul_f32_e32 v196, s86, v196
	v_mul_f32_e32 v197, s86, v197
	v_mul_f32_e32 v198, s86, v198
	v_mul_f32_e32 v199, s86, v199
	v_mul_f32_e32 v200, s86, v200
	v_mul_f32_e32 v201, s86, v201
	v_mul_f32_e32 v202, s86, v202
	v_mul_f32_e32 v203, s86, v203
	v_mul_f32_e32 v204, s86, v204
	v_mul_f32_e32 v205, s86, v205
	v_mul_f32_e32 v206, s86, v206
	v_mul_f32_e32 v207, s86, v207
	v_mul_f32_e32 v208, s86, v208
	v_mul_f32_e32 v209, s86, v209
	v_mul_f32_e32 v210, s86, v210
	v_mul_f32_e32 v211, s86, v211
	v_mul_f32_e32 v212, s86, v212
	v_mul_f32_e32 v213, s86, v213
	v_mul_f32_e32 v214, s86, v214
	v_mul_f32_e32 v215, s86, v215
	v_mul_f32_e32 v216, s86, v216
	v_mul_f32_e32 v217, s86, v217
	v_mul_f32_e32 v218, s86, v218
	v_mul_f32_e32 v219, s86, v219
	v_mul_f32_e32 v220, s86, v220
	v_mul_f32_e32 v221, s86, v221
	v_mul_f32_e32 v222, s86, v222
	v_mul_f32_e32 v223, s86, v223
	v_mul_f32_e32 v224, s86, v224
	v_mul_f32_e32 v225, s86, v225
	v_mul_f32_e32 v226, s86, v226
	v_mul_f32_e32 v227, s86, v227
	v_mul_f32_e32 v228, s86, v228
	v_mul_f32_e32 v229, s86, v229
	v_mul_f32_e32 v230, s86, v230
	v_mul_f32_e32 v231, s86, v231
	v_mul_f32_e32 v232, s86, v232
	v_mul_f32_e32 v233, s86, v233
	v_cvt_pk_fp8_f32 v236, v170, v171
	v_cvt_pk_fp8_f32 v237, v174, v175
	v_cvt_pk_fp8_f32 v238, v178, v179
	v_cvt_pk_fp8_f32 v239, v182, v183
	v_cvt_pk_fp8_f32 v240, v186, v187
	v_cvt_pk_fp8_f32 v241, v190, v191
	v_cvt_pk_fp8_f32 v242, v194, v195
	v_cvt_pk_fp8_f32 v243, v198, v199
	v_cvt_pk_fp8_f32 v244, v202, v203
	v_cvt_pk_fp8_f32 v245, v206, v207
	v_cvt_pk_fp8_f32 v246, v210, v211
	v_cvt_pk_fp8_f32 v247, v214, v215
	v_cvt_pk_fp8_f32 v248, v218, v219
	v_cvt_pk_fp8_f32 v249, v222, v223
	v_cvt_pk_fp8_f32 v250, v226, v227
	v_cvt_pk_fp8_f32 v251, v230, v231
	v_cvt_pk_fp8_f32 v236, v172, v173 op_sel:[0,0,1]
	v_cvt_pk_fp8_f32 v237, v176, v177 op_sel:[0,0,1]
	v_cvt_pk_fp8_f32 v238, v180, v181 op_sel:[0,0,1]
	v_cvt_pk_fp8_f32 v239, v184, v185 op_sel:[0,0,1]
	v_cvt_pk_fp8_f32 v240, v188, v189 op_sel:[0,0,1]
	v_cvt_pk_fp8_f32 v241, v192, v193 op_sel:[0,0,1]
	v_cvt_pk_fp8_f32 v242, v196, v197 op_sel:[0,0,1]
	v_cvt_pk_fp8_f32 v243, v200, v201 op_sel:[0,0,1]
	v_cvt_pk_fp8_f32 v244, v204, v205 op_sel:[0,0,1]
	v_cvt_pk_fp8_f32 v245, v208, v209 op_sel:[0,0,1]
	v_cvt_pk_fp8_f32 v246, v212, v213 op_sel:[0,0,1]
	v_cvt_pk_fp8_f32 v247, v216, v217 op_sel:[0,0,1]
	v_cvt_pk_fp8_f32 v248, v220, v221 op_sel:[0,0,1]
	v_cvt_pk_fp8_f32 v249, v224, v225 op_sel:[0,0,1]
	v_cvt_pk_fp8_f32 v250, v228, v229 op_sel:[0,0,1]
	v_cvt_pk_fp8_f32 v251, v232, v233 op_sel:[0,0,1]
	s_nop 0
	global_store_dword v235, v236, s[84:85]
	s_add_u32 s84, s84, 0x800
	s_addc_u32 s85, s85, 0
	global_store_dword v235, v237, s[84:85]
	s_add_u32 s84, s84, 0x800
	s_addc_u32 s85, s85, 0
	global_store_dword v235, v238, s[84:85]
	s_add_u32 s84, s84, 0x800
	s_addc_u32 s85, s85, 0
	global_store_dword v235, v239, s[84:85]
	s_add_u32 s84, s84, 0x800
	s_addc_u32 s85, s85, 0
	global_store_dword v235, v240, s[84:85]
	s_add_u32 s84, s84, 0x800
	s_addc_u32 s85, s85, 0
	global_store_dword v235, v241, s[84:85]
	s_add_u32 s84, s84, 0x800
	s_addc_u32 s85, s85, 0
	global_store_dword v235, v242, s[84:85]
	s_add_u32 s84, s84, 0x800
	s_addc_u32 s85, s85, 0
	global_store_dword v235, v243, s[84:85]
	s_add_u32 s84, s84, 0x800
	s_addc_u32 s85, s85, 0
	global_store_dword v235, v244, s[84:85]
	s_add_u32 s84, s84, 0x800
	s_addc_u32 s85, s85, 0
	global_store_dword v235, v245, s[84:85]
	s_add_u32 s84, s84, 0x800
	s_addc_u32 s85, s85, 0
	global_store_dword v235, v246, s[84:85]
	s_add_u32 s84, s84, 0x800
	s_addc_u32 s85, s85, 0
	global_store_dword v235, v247, s[84:85]
	s_add_u32 s84, s84, 0x800
	s_addc_u32 s85, s85, 0
	global_store_dword v235, v248, s[84:85]
	s_add_u32 s84, s84, 0x800
	s_addc_u32 s85, s85, 0
	global_store_dword v235, v249, s[84:85]
	s_add_u32 s84, s84, 0x800
	s_addc_u32 s85, s85, 0
	global_store_dword v235, v250, s[84:85]
	s_add_u32 s84, s84, 0x800
	s_addc_u32 s85, s85, 0
	global_store_dword v235, v251, s[84:85]
	s_barrier
	global_load_dwordx4 v[44:47], v[6:7], off offset:-4096
	global_load_dwordx4 v[36:39], v[6:7], off
	v_add_co_u32_e32 v6, vcc, s38, v4
	s_lshl_b32 s24, s28, 3
	s_nop 0
	v_addc_co_u32_e32 v7, vcc, 0, v5, vcc
	global_load_dwordx4 v[40:43], v[6:7], off offset:-4096
	global_load_dwordx4 v[28:31], v[6:7], off
	v_add_co_u32_e32 v6, vcc, s37, v4
	s_andn2_b32 s24, s24, 63
	s_nop 0
	v_addc_co_u32_e32 v7, vcc, 0, v5, vcc
	global_load_dwordx4 v[32:35], v[6:7], off offset:-4096
	global_load_dwordx4 v[20:23], v[6:7], off
	v_add_co_u32_e32 v6, vcc, s36, v4
	s_nop 1
	v_addc_co_u32_e32 v7, vcc, 0, v5, vcc
	global_load_dwordx4 v[48:51], v[4:5], off
	global_load_dwordx4 v[24:27], v[6:7], off
	v_add_u32_e32 v4, s24, v84
	v_ashrrev_i32_e32 v5, 31, v4
	v_lshlrev_b64 v[4:5], 12, v[4:5]
	v_lshl_add_u64 v[4:5], s[16:17], 0, v[4:5]
	s_lshl_b32 s24, s29, 9
	v_lshl_add_u64 v[4:5], v[4:5], 0, s[24:25]
	v_lshl_add_u64 v[4:5], v[4:5], 0, v[60:61]
	global_load_dwordx4 v[16:19], v[4:5], off
	global_load_dwordx4 v[12:15], v[4:5], off offset:64
	global_load_dwordx4 v[8:11], v[4:5], off offset:128
	s_nop 0
	global_load_dwordx4 v[4:7], v[4:5], off offset:192
	ds_read_b128 v[102:105], v87 offset:34816
	ds_read_b128 v[106:109], v87 offset:34832
	ds_read_b128 v[110:113], v87 offset:34848
	ds_read_b128 v[114:117], v87 offset:34864
	s_waitcnt lgkmcnt(3)
	v_max_u32_e32 v61, v102, v103
	v_max_u32_e32 v77, v104, v105
	s_waitcnt lgkmcnt(2)
	v_max_u32_e32 v78, v108, v109
	ds_read_b128 v[102:105], v87 offset:34880
	v_max3_u32 v78, v106, v107, v78
	ds_read_b128 v[106:109], v87 offset:34896
	v_max3_u32 v61, v61, v77, v78
	s_waitcnt lgkmcnt(3)
	v_max_u32_e32 v77, v112, v113
	s_waitcnt lgkmcnt(2)
	v_max_u32_e32 v78, v116, v117
	v_max3_u32 v77, v110, v111, v77
	v_max3_u32 v78, v114, v115, v78
	v_max3_u32 v61, v61, v77, v78
	s_waitcnt lgkmcnt(1)
	v_max_u32_e32 v77, v104, v105
	v_max3_u32 v77, v102, v103, v77
	ds_read_b128 v[102:105], v87 offset:34912
	s_waitcnt lgkmcnt(1)
	v_max_u32_e32 v78, v108, v109
	ds_read_b128 v[108:111], v87 offset:34928
	v_max3_u32 v78, v106, v107, v78
	v_max3_u32 v61, v61, v77, v78
	s_waitcnt lgkmcnt(1)
	v_max_u32_e32 v77, v104, v105
	v_max3_u32 v77, v102, v103, v77
	s_waitcnt lgkmcnt(0)
	v_max_u32_e32 v78, v110, v111
	v_max3_u32 v78, v108, v109, v78
	v_max3_u32 v112, v61, v77, v78
	s_nop 1
	v_mov_b32_dpp v61, v112 quad_perm:[1,0,3,2] row_mask:0xf bank_mask:0xf
	s_waitcnt lgkmcnt(0)
	v_max_u32_e32 v61, v112, v61
	s_nop 1
	v_mov_b32_dpp v77, v61 quad_perm:[2,3,0,1] row_mask:0xf bank_mask:0xf
	s_waitcnt lgkmcnt(0)
	v_max_u32_e32 v61, v61, v77
	v_not_b32_e32 v77, v61
	v_bfe_u32 v77, v77, 5, 2
	v_cmp_eq_u32_e32 vcc, v77, v83
	s_and_saveexec_b64 s[28:29], vcc
	s_cbranch_execz .LBB0_763
	v_bitop3_b32 v77, v61, s44, v61 bitop3:0xc
	v_lshl_add_u32 v78, v77, 2, v85
	ds_write_b32 v78, v53 offset:34816
	ds_write_b8 v86, v77 offset:16
	ds_read_b128 v[102:105], v87 offset:34816
	ds_read_b128 v[106:109], v87 offset:34832
	ds_read_b128 v[110:113], v87 offset:34848
	ds_read_b128 v[114:117], v87 offset:34864
	ds_read_b128 v[118:121], v87 offset:34880
	ds_read_b128 v[122:125], v87 offset:34896
	ds_read_b128 v[126:129], v87 offset:34912
	ds_read_b128 v[130:133], v87 offset:34928
	s_waitcnt lgkmcnt(6)
	v_max_u32_e32 v80, v108, v109
	v_max_u32_e32 v77, v102, v103
	v_max_u32_e32 v78, v104, v105
	v_max3_u32 v80, v106, v107, v80
	v_max3_u32 v77, v77, v78, v80
	s_waitcnt lgkmcnt(5)
	v_max_u32_e32 v78, v112, v113
	s_waitcnt lgkmcnt(4)
	v_max_u32_e32 v80, v116, v117
	v_max3_u32 v78, v110, v111, v78
	v_max3_u32 v80, v114, v115, v80
	v_max3_u32 v77, v77, v78, v80
	s_waitcnt lgkmcnt(3)
	v_max_u32_e32 v78, v120, v121
	s_waitcnt lgkmcnt(2)
	v_max_u32_e32 v80, v124, v125
	v_max3_u32 v78, v118, v119, v78
	v_max3_u32 v80, v122, v123, v80
	v_max3_u32 v77, v77, v78, v80
	s_waitcnt lgkmcnt(1)
	v_max_u32_e32 v78, v128, v129
	s_waitcnt lgkmcnt(0)
	v_max_u32_e32 v80, v132, v133
	v_max3_u32 v78, v126, v127, v78
	v_max3_u32 v80, v130, v131, v80
	v_max3_u32 v112, v77, v78, v80
